# workgroups with no tile in a second-GEMM item skip that item's token wait and cache invalidate (they read nothing); they still arrive
# speedup vs baseline: 1.0030x; 1.0021x over previous
.LBB0_340:
	s_mov_b32 s26, s63
	v_readlane_b32 s32, v255, 0
	s_sub_i32 s32, s32, s59
	v_mov_b32_e32 v232, s32
	v_readlane_b32 s32, v255, 16
	v_ashrrev_i32_e32 v233, 31, v232
	s_nop 0
	v_and_b32_e32 v233, s32, v233
	v_add_u32_e32 v232, v232, v233
	s_nop 0
	v_readfirstlane_b32 s32, v232
	s_cmpk_gt_i32 s32, 0x7f
	s_cbranch_scc0 .Lbyp_no
	s_xor_b64 s[12:13], s[8:9], -1
	s_branch .LBB0_407
.Lbyp_no:
	s_cmp_lt_i32 s63, 2
	s_cbranch_scc1 .LBB0_358
	v_readlane_b32 s6, v255, 10
	v_readlane_b32 s7, v255, 11
	s_and_b64 vcc, exec, s[6:7]
	s_cbranch_vccnz .LBB0_357
	v_mbcnt_lo_u32_b32 v0, -1, 0
	v_mbcnt_hi_u32_b32 v0, -1, v0
	s_nop 0
	v_cmp_eq_u32_e32 vcc, 0, v0
	s_and_saveexec_b64 s[6:7], vcc
	s_cbranch_execz .LBB0_356
	s_add_i32 s3, s26, -2
	s_mul_hi_u32 s10, s3, 0x220
	s_mulk_i32 s3, 0x220
	v_readlane_b32 s11, v255, 12
	s_add_u32 s12, s11, s3
	v_readlane_b32 s3, v255, 13
	s_addc_u32 s13, s3, s10
	v_readlane_b32 s3, v255, 17
	s_nop 0
	v_mov_b64_e32 v[2:3], s[12:13]
	v_mov_b32_e32 v0, s3
	ds_read_b32 v0, v0
	flat_load_dword v2, v[2:3] offset:512 sc1
	s_waitcnt vmcnt(0) lgkmcnt(0)
	v_cmp_lt_u32_e32 vcc, v2, v0
	s_and_saveexec_b64 s[10:11], vcc
	s_cbranch_execz .LBB0_355
	s_mov_b32 s3, 1
	s_mov_b64 s[14:15], 0
	s_branch .LBB0_346
